# gain weight transposes: all 32+32 loads of an item issued together (one round trip per item instead of four); rope pipelining and gMLP staging fix kept
# speedup vs baseline: 1.0105x; 1.0001x over previous
; DI void transpose_item(const float* W, const float* gain, int K, int Ns, int Nd, int mat, bf16_t* WT, LAS float* scr, int item, int lane) {
;     ...
; #pragma unroll 8
;     for (int i = 0; i < 32; ++i) { const int kk = 2 * i + (lane >> 5); float v = 0.f; if (sc >= 0) v = W[(size_t)(k0 + kk) * Ns + sc]; if (gain) v *= gain[k0 + kk]; scr[kk * 33 + (lane & 31)] = v; }
.LBB0_38:
	v_mov_b32_e32 v100, 0
	v_mov_b32_e32 v101, 0
	v_mov_b32_e32 v102, 0
	v_mov_b32_e32 v103, 0
	v_mov_b32_e32 v104, 0
	v_mov_b32_e32 v105, 0
	v_mov_b32_e32 v106, 0
	v_mov_b32_e32 v107, 0
	v_mov_b32_e32 v108, 0
	v_mov_b32_e32 v109, 0
	v_mov_b32_e32 v110, 0
	v_mov_b32_e32 v111, 0
	v_mov_b32_e32 v112, 0
	v_mov_b32_e32 v113, 0
	v_mov_b32_e32 v114, 0
	v_mov_b32_e32 v115, 0
	v_mov_b32_e32 v116, 0
	v_mov_b32_e32 v117, 0
	v_mov_b32_e32 v118, 0
	v_mov_b32_e32 v119, 0
	v_mov_b32_e32 v120, 0
	v_mov_b32_e32 v121, 0
	v_mov_b32_e32 v122, 0
	v_mov_b32_e32 v123, 0
	v_mov_b32_e32 v124, 0
	v_mov_b32_e32 v125, 0
	v_mov_b32_e32 v126, 0
	v_mov_b32_e32 v127, 0
	v_mov_b32_e32 v128, 0
	v_mov_b32_e32 v129, 0
	v_mov_b32_e32 v130, 0
	v_mov_b32_e32 v131, 0
	v_lshl_add_u64 v[164:165], v[38:39], 0, s[6:7]
	global_load_dword v100, v[164:165], off
	v_lshl_add_u64 v[164:165], v[36:37], 0, s[6:7]
	global_load_dword v101, v[164:165], off
	v_lshl_add_u64 v[164:165], v[34:35], 0, s[6:7]
	global_load_dword v102, v[164:165], off
	v_lshl_add_u64 v[164:165], v[32:33], 0, s[6:7]
	global_load_dword v103, v[164:165], off
	v_lshl_add_u64 v[164:165], v[30:31], 0, s[6:7]
	global_load_dword v104, v[164:165], off
	v_lshl_add_u64 v[164:165], v[28:29], 0, s[6:7]
	global_load_dword v105, v[164:165], off
	v_lshl_add_u64 v[164:165], v[26:27], 0, s[6:7]
	global_load_dword v106, v[164:165], off
	v_lshl_add_u64 v[164:165], v[24:25], 0, s[6:7]
	global_load_dword v107, v[164:165], off
	s_add_u32 s6, s6, 0x10000
	s_addc_u32 s7, s7, 0
	v_lshl_add_u64 v[164:165], v[38:39], 0, s[6:7]
	global_load_dword v108, v[164:165], off
	v_lshl_add_u64 v[164:165], v[36:37], 0, s[6:7]
	global_load_dword v109, v[164:165], off
	v_lshl_add_u64 v[164:165], v[34:35], 0, s[6:7]
	global_load_dword v110, v[164:165], off
	v_lshl_add_u64 v[164:165], v[32:33], 0, s[6:7]
	global_load_dword v111, v[164:165], off
	v_lshl_add_u64 v[164:165], v[30:31], 0, s[6:7]
	global_load_dword v112, v[164:165], off
	v_lshl_add_u64 v[164:165], v[28:29], 0, s[6:7]
	global_load_dword v113, v[164:165], off
	v_lshl_add_u64 v[164:165], v[26:27], 0, s[6:7]
	global_load_dword v114, v[164:165], off
	v_lshl_add_u64 v[164:165], v[24:25], 0, s[6:7]
	global_load_dword v115, v[164:165], off
	s_add_u32 s6, s6, 0x10000
	s_addc_u32 s7, s7, 0
	v_lshl_add_u64 v[164:165], v[38:39], 0, s[6:7]
	global_load_dword v116, v[164:165], off
	v_lshl_add_u64 v[164:165], v[36:37], 0, s[6:7]
	global_load_dword v117, v[164:165], off
	v_lshl_add_u64 v[164:165], v[34:35], 0, s[6:7]
	global_load_dword v118, v[164:165], off
	v_lshl_add_u64 v[164:165], v[32:33], 0, s[6:7]
	global_load_dword v119, v[164:165], off
	v_lshl_add_u64 v[164:165], v[30:31], 0, s[6:7]
	global_load_dword v120, v[164:165], off
	v_lshl_add_u64 v[164:165], v[28:29], 0, s[6:7]
	global_load_dword v121, v[164:165], off
	v_lshl_add_u64 v[164:165], v[26:27], 0, s[6:7]
	global_load_dword v122, v[164:165], off
	v_lshl_add_u64 v[164:165], v[24:25], 0, s[6:7]
	global_load_dword v123, v[164:165], off
	s_add_u32 s6, s6, 0x10000
	s_addc_u32 s7, s7, 0
	v_lshl_add_u64 v[164:165], v[38:39], 0, s[6:7]
	global_load_dword v124, v[164:165], off
	v_lshl_add_u64 v[164:165], v[36:37], 0, s[6:7]
	global_load_dword v125, v[164:165], off
	v_lshl_add_u64 v[164:165], v[34:35], 0, s[6:7]
	global_load_dword v126, v[164:165], off
	v_lshl_add_u64 v[164:165], v[32:33], 0, s[6:7]
	global_load_dword v127, v[164:165], off
	v_lshl_add_u64 v[164:165], v[30:31], 0, s[6:7]
	global_load_dword v128, v[164:165], off
	v_lshl_add_u64 v[164:165], v[28:29], 0, s[6:7]
	global_load_dword v129, v[164:165], off
	v_lshl_add_u64 v[164:165], v[26:27], 0, s[6:7]
	global_load_dword v130, v[164:165], off
	v_lshl_add_u64 v[164:165], v[24:25], 0, s[6:7]
	global_load_dword v131, v[164:165], off
	s_add_u32 s6, s6, 0x10000
	s_addc_u32 s7, s7, 0
	s_andn2_b64 vcc, exec, s[22:23]
	s_cbranch_vccnz .Ltp1_g
	v_lshl_add_u64 v[164:165], s[8:9], 0, v[2:3]
	global_load_dword v132, v[164:165], off
	global_load_dword v140, v[164:165], off offset:64
	global_load_dword v148, v[164:165], off offset:128
	global_load_dword v156, v[164:165], off offset:192
	v_lshl_add_u64 v[164:165], s[8:9], 0, v[22:23]
	global_load_dword v133, v[164:165], off offset:8
	global_load_dword v134, v[164:165], off offset:16
	global_load_dword v135, v[164:165], off offset:24
	global_load_dword v136, v[164:165], off offset:32
	global_load_dword v137, v[164:165], off offset:40
	global_load_dword v138, v[164:165], off offset:48
	global_load_dword v139, v[164:165], off offset:56
	global_load_dword v141, v[164:165], off offset:72
	global_load_dword v142, v[164:165], off offset:80
	global_load_dword v143, v[164:165], off offset:88
	global_load_dword v144, v[164:165], off offset:96
	global_load_dword v145, v[164:165], off offset:104
	global_load_dword v146, v[164:165], off offset:112
	global_load_dword v147, v[164:165], off offset:120
	global_load_dword v149, v[164:165], off offset:136
	global_load_dword v150, v[164:165], off offset:144
	global_load_dword v151, v[164:165], off offset:152
	global_load_dword v152, v[164:165], off offset:160
	global_load_dword v153, v[164:165], off offset:168
	global_load_dword v154, v[164:165], off offset:176
	global_load_dword v155, v[164:165], off offset:184
	global_load_dword v157, v[164:165], off offset:200
	global_load_dword v158, v[164:165], off offset:208
	global_load_dword v159, v[164:165], off offset:216
	global_load_dword v160, v[164:165], off offset:224
	global_load_dword v161, v[164:165], off offset:232
	global_load_dword v162, v[164:165], off offset:240
	global_load_dword v163, v[164:165], off offset:248
	s_waitcnt vmcnt(0)
	v_mul_f32_e32 v100, v100, v132
	v_mul_f32_e32 v101, v101, v133
	v_mul_f32_e32 v102, v102, v134
	v_mul_f32_e32 v103, v103, v135
	v_mul_f32_e32 v104, v104, v136
	v_mul_f32_e32 v105, v105, v137
	v_mul_f32_e32 v106, v106, v138
	v_mul_f32_e32 v107, v107, v139
	v_mul_f32_e32 v108, v108, v140
	v_mul_f32_e32 v109, v109, v141
	v_mul_f32_e32 v110, v110, v142
	v_mul_f32_e32 v111, v111, v143
	v_mul_f32_e32 v112, v112, v144
	v_mul_f32_e32 v113, v113, v145
	v_mul_f32_e32 v114, v114, v146
	v_mul_f32_e32 v115, v115, v147
	v_mul_f32_e32 v116, v116, v148
	v_mul_f32_e32 v117, v117, v149
	v_mul_f32_e32 v118, v118, v150
	v_mul_f32_e32 v119, v119, v151
	v_mul_f32_e32 v120, v120, v152
	v_mul_f32_e32 v121, v121, v153
	v_mul_f32_e32 v122, v122, v154
	v_mul_f32_e32 v123, v123, v155
	v_mul_f32_e32 v124, v124, v156
	v_mul_f32_e32 v125, v125, v157
	v_mul_f32_e32 v126, v126, v158
	v_mul_f32_e32 v127, v127, v159
	v_mul_f32_e32 v128, v128, v160
	v_mul_f32_e32 v129, v129, v161
	v_mul_f32_e32 v130, v130, v162
	v_mul_f32_e32 v131, v131, v163
; DI void transpose_item(const float* W, const float* gain, int K, int Ns, int Nd, int mat, bf16_t* WT, LAS float* scr, int item, int lane) {
;     ...
;     for (int i = 0; i < 32; ++i) { const int kk = 2 * i + (lane >> 5); float v = 0.f; if (sc >= 0) v = W[(size_t)(k0 + kk) * Ns + sc]; if (gain) v *= gain[k0 + kk]; scr[kk * 33 + (lane & 31)] = v; }
.Ltp1_g:
	s_waitcnt vmcnt(0)
	ds_write_b32 v42, v100
	ds_write_b32 v42, v101 offset:264
	ds_write_b32 v42, v102 offset:528
	ds_write_b32 v42, v103 offset:792
	ds_write_b32 v42, v104 offset:1056
	ds_write_b32 v42, v105 offset:1320
	ds_write_b32 v42, v106 offset:1584
	ds_write_b32 v42, v107 offset:1848
	ds_write_b32 v42, v108 offset:2112
	ds_write_b32 v42, v109 offset:2376
	ds_write_b32 v42, v110 offset:2640
	ds_write_b32 v42, v111 offset:2904
	ds_write_b32 v42, v112 offset:3168
	ds_write_b32 v42, v113 offset:3432
	ds_write_b32 v42, v114 offset:3696
	ds_write_b32 v42, v115 offset:3960
	ds_write_b32 v42, v116 offset:4224
	ds_write_b32 v42, v117 offset:4488
	ds_write_b32 v42, v118 offset:4752
	ds_write_b32 v42, v119 offset:5016
	ds_write_b32 v42, v120 offset:5280
	ds_write_b32 v42, v121 offset:5544
	ds_write_b32 v42, v122 offset:5808
	ds_write_b32 v42, v123 offset:6072
	ds_write_b32 v42, v124 offset:6336
	ds_write_b32 v42, v125 offset:6600
	ds_write_b32 v42, v126 offset:6864
	ds_write_b32 v42, v127 offset:7128
	ds_write_b32 v42, v128 offset:7392
	ds_write_b32 v42, v129 offset:7656
	ds_write_b32 v42, v130 offset:7920
	ds_write_b32 v42, v131 offset:8184
	s_add_u32 s8, s8, 0x100
	s_addc_u32 s9, s9, 0
	v_add_u32_e32 v42, 0x2100, v42
	s_cmp_lg_u32 s6, 0x40000
	s_branch .LBB0_54

; DI void transpose_item(const float* W, const float* gain, int K, int Ns, int Nd, int mat, bf16_t* WT, LAS float* scr, int item, int lane) {
;     ...
; #pragma unroll 8
;     for (int i = 0; i < 32; ++i) { const int kk = 2 * i + (lane >> 5); float v = 0.f; if (sc >= 0) v = W[(size_t)(k0 + kk) * Ns + sc]; if (gain) v *= gain[k0 + kk]; scr[kk * 33 + (lane & 31)] = v; }
.LBB0_63:
	v_mov_b32_e32 v100, 0
	v_mov_b32_e32 v101, 0
	v_mov_b32_e32 v102, 0
	v_mov_b32_e32 v103, 0
	v_mov_b32_e32 v104, 0
	v_mov_b32_e32 v105, 0
	v_mov_b32_e32 v106, 0
	v_mov_b32_e32 v107, 0
	v_mov_b32_e32 v108, 0
	v_mov_b32_e32 v109, 0
	v_mov_b32_e32 v110, 0
	v_mov_b32_e32 v111, 0
	v_mov_b32_e32 v112, 0
	v_mov_b32_e32 v113, 0
	v_mov_b32_e32 v114, 0
	v_mov_b32_e32 v115, 0
	v_mov_b32_e32 v116, 0
	v_mov_b32_e32 v117, 0
	v_mov_b32_e32 v118, 0
	v_mov_b32_e32 v119, 0
	v_mov_b32_e32 v120, 0
	v_mov_b32_e32 v121, 0
	v_mov_b32_e32 v122, 0
	v_mov_b32_e32 v123, 0
	v_mov_b32_e32 v124, 0
	v_mov_b32_e32 v125, 0
	v_mov_b32_e32 v126, 0
	v_mov_b32_e32 v127, 0
	v_mov_b32_e32 v128, 0
	v_mov_b32_e32 v129, 0
	v_mov_b32_e32 v130, 0
	v_mov_b32_e32 v131, 0
	v_lshl_add_u64 v[164:165], v[38:39], 0, s[6:7]
	global_load_dword v100, v[164:165], off
	v_lshl_add_u64 v[164:165], v[36:37], 0, s[6:7]
	global_load_dword v101, v[164:165], off
	v_lshl_add_u64 v[164:165], v[34:35], 0, s[6:7]
	global_load_dword v102, v[164:165], off
	v_lshl_add_u64 v[164:165], v[32:33], 0, s[6:7]
	global_load_dword v103, v[164:165], off
	v_lshl_add_u64 v[164:165], v[30:31], 0, s[6:7]
	global_load_dword v104, v[164:165], off
	v_lshl_add_u64 v[164:165], v[28:29], 0, s[6:7]
	global_load_dword v105, v[164:165], off
	v_lshl_add_u64 v[164:165], v[26:27], 0, s[6:7]
	global_load_dword v106, v[164:165], off
	v_lshl_add_u64 v[164:165], v[24:25], 0, s[6:7]
	global_load_dword v107, v[164:165], off
	s_add_u32 s6, s6, 0x20000
	s_addc_u32 s7, s7, 0
	v_lshl_add_u64 v[164:165], v[38:39], 0, s[6:7]
	global_load_dword v108, v[164:165], off
	v_lshl_add_u64 v[164:165], v[36:37], 0, s[6:7]
	global_load_dword v109, v[164:165], off
	v_lshl_add_u64 v[164:165], v[34:35], 0, s[6:7]
	global_load_dword v110, v[164:165], off
	v_lshl_add_u64 v[164:165], v[32:33], 0, s[6:7]
	global_load_dword v111, v[164:165], off
	v_lshl_add_u64 v[164:165], v[30:31], 0, s[6:7]
	global_load_dword v112, v[164:165], off
	v_lshl_add_u64 v[164:165], v[28:29], 0, s[6:7]
	global_load_dword v113, v[164:165], off
	v_lshl_add_u64 v[164:165], v[26:27], 0, s[6:7]
	global_load_dword v114, v[164:165], off
	v_lshl_add_u64 v[164:165], v[24:25], 0, s[6:7]
	global_load_dword v115, v[164:165], off
	s_add_u32 s6, s6, 0x20000
	s_addc_u32 s7, s7, 0
	v_lshl_add_u64 v[164:165], v[38:39], 0, s[6:7]
	global_load_dword v116, v[164:165], off
	v_lshl_add_u64 v[164:165], v[36:37], 0, s[6:7]
	global_load_dword v117, v[164:165], off
	v_lshl_add_u64 v[164:165], v[34:35], 0, s[6:7]
	global_load_dword v118, v[164:165], off
	v_lshl_add_u64 v[164:165], v[32:33], 0, s[6:7]
	global_load_dword v119, v[164:165], off
	v_lshl_add_u64 v[164:165], v[30:31], 0, s[6:7]
	global_load_dword v120, v[164:165], off
	v_lshl_add_u64 v[164:165], v[28:29], 0, s[6:7]
	global_load_dword v121, v[164:165], off
	v_lshl_add_u64 v[164:165], v[26:27], 0, s[6:7]
	global_load_dword v122, v[164:165], off
	v_lshl_add_u64 v[164:165], v[24:25], 0, s[6:7]
	global_load_dword v123, v[164:165], off
	s_add_u32 s6, s6, 0x20000
	s_addc_u32 s7, s7, 0
	v_lshl_add_u64 v[164:165], v[38:39], 0, s[6:7]
	global_load_dword v124, v[164:165], off
	v_lshl_add_u64 v[164:165], v[36:37], 0, s[6:7]
	global_load_dword v125, v[164:165], off
	v_lshl_add_u64 v[164:165], v[34:35], 0, s[6:7]
	global_load_dword v126, v[164:165], off
	v_lshl_add_u64 v[164:165], v[32:33], 0, s[6:7]
	global_load_dword v127, v[164:165], off
	v_lshl_add_u64 v[164:165], v[30:31], 0, s[6:7]
	global_load_dword v128, v[164:165], off
	v_lshl_add_u64 v[164:165], v[28:29], 0, s[6:7]
	global_load_dword v129, v[164:165], off
	v_lshl_add_u64 v[164:165], v[26:27], 0, s[6:7]
	global_load_dword v130, v[164:165], off
	v_lshl_add_u64 v[164:165], v[24:25], 0, s[6:7]
	global_load_dword v131, v[164:165], off
	s_add_u32 s6, s6, 0x20000
	s_addc_u32 s7, s7, 0
	s_andn2_b64 vcc, exec, s[22:23]
	s_cbranch_vccnz .Ltp2_g
	v_lshl_add_u64 v[164:165], s[8:9], 0, v[2:3]
	global_load_dword v132, v[164:165], off
	global_load_dword v140, v[164:165], off offset:64
	global_load_dword v148, v[164:165], off offset:128
	global_load_dword v156, v[164:165], off offset:192
	v_lshl_add_u64 v[164:165], s[8:9], 0, v[22:23]
	global_load_dword v133, v[164:165], off offset:8
	global_load_dword v134, v[164:165], off offset:16
	global_load_dword v135, v[164:165], off offset:24
	global_load_dword v136, v[164:165], off offset:32
	global_load_dword v137, v[164:165], off offset:40
	global_load_dword v138, v[164:165], off offset:48
	global_load_dword v139, v[164:165], off offset:56
	global_load_dword v141, v[164:165], off offset:72
	global_load_dword v142, v[164:165], off offset:80
	global_load_dword v143, v[164:165], off offset:88
	global_load_dword v144, v[164:165], off offset:96
	global_load_dword v145, v[164:165], off offset:104
	global_load_dword v146, v[164:165], off offset:112
	global_load_dword v147, v[164:165], off offset:120
	global_load_dword v149, v[164:165], off offset:136
	global_load_dword v150, v[164:165], off offset:144
	global_load_dword v151, v[164:165], off offset:152
	global_load_dword v152, v[164:165], off offset:160
	global_load_dword v153, v[164:165], off offset:168
	global_load_dword v154, v[164:165], off offset:176
	global_load_dword v155, v[164:165], off offset:184
	global_load_dword v157, v[164:165], off offset:200
	global_load_dword v158, v[164:165], off offset:208
	global_load_dword v159, v[164:165], off offset:216
	global_load_dword v160, v[164:165], off offset:224
	global_load_dword v161, v[164:165], off offset:232
	global_load_dword v162, v[164:165], off offset:240
	global_load_dword v163, v[164:165], off offset:248
	s_waitcnt vmcnt(0)
	v_mul_f32_e32 v100, v100, v132
	v_mul_f32_e32 v101, v101, v133
	v_mul_f32_e32 v102, v102, v134
	v_mul_f32_e32 v103, v103, v135
	v_mul_f32_e32 v104, v104, v136
	v_mul_f32_e32 v105, v105, v137
	v_mul_f32_e32 v106, v106, v138
	v_mul_f32_e32 v107, v107, v139
	v_mul_f32_e32 v108, v108, v140
	v_mul_f32_e32 v109, v109, v141
	v_mul_f32_e32 v110, v110, v142
	v_mul_f32_e32 v111, v111, v143
	v_mul_f32_e32 v112, v112, v144
	v_mul_f32_e32 v113, v113, v145
	v_mul_f32_e32 v114, v114, v146
	v_mul_f32_e32 v115, v115, v147
	v_mul_f32_e32 v116, v116, v148
	v_mul_f32_e32 v117, v117, v149
	v_mul_f32_e32 v118, v118, v150
	v_mul_f32_e32 v119, v119, v151
	v_mul_f32_e32 v120, v120, v152
	v_mul_f32_e32 v121, v121, v153
	v_mul_f32_e32 v122, v122, v154
	v_mul_f32_e32 v123, v123, v155
	v_mul_f32_e32 v124, v124, v156
	v_mul_f32_e32 v125, v125, v157
	v_mul_f32_e32 v126, v126, v158
	v_mul_f32_e32 v127, v127, v159
	v_mul_f32_e32 v128, v128, v160
	v_mul_f32_e32 v129, v129, v161
	v_mul_f32_e32 v130, v130, v162
	v_mul_f32_e32 v131, v131, v163
; DI void transpose_item(const float* W, const float* gain, int K, int Ns, int Nd, int mat, bf16_t* WT, LAS float* scr, int item, int lane) {
;     ...
;     for (int i = 0; i < 32; ++i) { const int kk = 2 * i + (lane >> 5); float v = 0.f; if (sc >= 0) v = W[(size_t)(k0 + kk) * Ns + sc]; if (gain) v *= gain[k0 + kk]; scr[kk * 33 + (lane & 31)] = v; }
.Ltp2_g:
	s_waitcnt vmcnt(0)
	ds_write_b32 v42, v100
	ds_write_b32 v42, v101 offset:264
	ds_write_b32 v42, v102 offset:528
	ds_write_b32 v42, v103 offset:792
	ds_write_b32 v42, v104 offset:1056
	ds_write_b32 v42, v105 offset:1320
	ds_write_b32 v42, v106 offset:1584
	ds_write_b32 v42, v107 offset:1848
	ds_write_b32 v42, v108 offset:2112
	ds_write_b32 v42, v109 offset:2376
	ds_write_b32 v42, v110 offset:2640
	ds_write_b32 v42, v111 offset:2904
	ds_write_b32 v42, v112 offset:3168
	ds_write_b32 v42, v113 offset:3432
	ds_write_b32 v42, v114 offset:3696
	ds_write_b32 v42, v115 offset:3960
	ds_write_b32 v42, v116 offset:4224
	ds_write_b32 v42, v117 offset:4488
	ds_write_b32 v42, v118 offset:4752
	ds_write_b32 v42, v119 offset:5016
	ds_write_b32 v42, v120 offset:5280
	ds_write_b32 v42, v121 offset:5544
	ds_write_b32 v42, v122 offset:5808
	ds_write_b32 v42, v123 offset:6072
	ds_write_b32 v42, v124 offset:6336
	ds_write_b32 v42, v125 offset:6600
	ds_write_b32 v42, v126 offset:6864
	ds_write_b32 v42, v127 offset:7128
	ds_write_b32 v42, v128 offset:7392
	ds_write_b32 v42, v129 offset:7656
	ds_write_b32 v42, v130 offset:7920
	ds_write_b32 v42, v131 offset:8184
	s_add_u32 s8, s8, 0x100
	s_addc_u32 s9, s9, 0
	v_add_u32_e32 v42, 0x2100, v42
	s_cmp_lg_u32 s6, 0x80000
	s_branch .LBB0_79

; DI void transpose_item(const float* W, const float* gain, int K, int Ns, int Nd, int mat, bf16_t* WT, LAS float* scr, int item, int lane) {
;     ...
; #pragma unroll 8
;     for (int i = 0; i < 32; ++i) { const int kk = 2 * i + (lane >> 5); float v = 0.f; if (sc >= 0) v = W[(size_t)(k0 + kk) * Ns + sc]; if (gain) v *= gain[k0 + kk]; scr[kk * 33 + (lane & 31)] = v; }
.LBB0_88:
	v_mov_b32_e32 v100, 0
	v_mov_b32_e32 v101, 0
	v_mov_b32_e32 v102, 0
	v_mov_b32_e32 v103, 0
	v_mov_b32_e32 v104, 0
	v_mov_b32_e32 v105, 0
	v_mov_b32_e32 v106, 0
	v_mov_b32_e32 v107, 0
	v_mov_b32_e32 v108, 0
	v_mov_b32_e32 v109, 0
	v_mov_b32_e32 v110, 0
	v_mov_b32_e32 v111, 0
	v_mov_b32_e32 v112, 0
	v_mov_b32_e32 v113, 0
	v_mov_b32_e32 v114, 0
	v_mov_b32_e32 v115, 0
	v_mov_b32_e32 v116, 0
	v_mov_b32_e32 v117, 0
	v_mov_b32_e32 v118, 0
	v_mov_b32_e32 v119, 0
	v_mov_b32_e32 v120, 0
	v_mov_b32_e32 v121, 0
	v_mov_b32_e32 v122, 0
	v_mov_b32_e32 v123, 0
	v_mov_b32_e32 v124, 0
	v_mov_b32_e32 v125, 0
	v_mov_b32_e32 v126, 0
	v_mov_b32_e32 v127, 0
	v_mov_b32_e32 v128, 0
	v_mov_b32_e32 v129, 0
	v_mov_b32_e32 v130, 0
	v_mov_b32_e32 v131, 0
	v_lshl_add_u64 v[164:165], v[38:39], 0, s[6:7]
	global_load_dword v100, v[164:165], off
	v_lshl_add_u64 v[164:165], v[36:37], 0, s[6:7]
	global_load_dword v101, v[164:165], off
	v_lshl_add_u64 v[164:165], v[34:35], 0, s[6:7]
	global_load_dword v102, v[164:165], off
	v_lshl_add_u64 v[164:165], v[32:33], 0, s[6:7]
	global_load_dword v103, v[164:165], off
	v_lshl_add_u64 v[164:165], v[30:31], 0, s[6:7]
	global_load_dword v104, v[164:165], off
	v_lshl_add_u64 v[164:165], v[28:29], 0, s[6:7]
	global_load_dword v105, v[164:165], off
	v_lshl_add_u64 v[164:165], v[26:27], 0, s[6:7]
	global_load_dword v106, v[164:165], off
	v_lshl_add_u64 v[164:165], v[22:23], 0, s[6:7]
	global_load_dword v107, v[164:165], off
	s_add_u32 s6, s6, 0x18000
	s_addc_u32 s7, s7, 0
	v_lshl_add_u64 v[164:165], v[38:39], 0, s[6:7]
	global_load_dword v108, v[164:165], off
	v_lshl_add_u64 v[164:165], v[36:37], 0, s[6:7]
	global_load_dword v109, v[164:165], off
	v_lshl_add_u64 v[164:165], v[34:35], 0, s[6:7]
	global_load_dword v110, v[164:165], off
	v_lshl_add_u64 v[164:165], v[32:33], 0, s[6:7]
	global_load_dword v111, v[164:165], off
	v_lshl_add_u64 v[164:165], v[30:31], 0, s[6:7]
	global_load_dword v112, v[164:165], off
	v_lshl_add_u64 v[164:165], v[28:29], 0, s[6:7]
	global_load_dword v113, v[164:165], off
	v_lshl_add_u64 v[164:165], v[26:27], 0, s[6:7]
	global_load_dword v114, v[164:165], off
	v_lshl_add_u64 v[164:165], v[22:23], 0, s[6:7]
	global_load_dword v115, v[164:165], off
	s_add_u32 s6, s6, 0x18000
	s_addc_u32 s7, s7, 0
	v_lshl_add_u64 v[164:165], v[38:39], 0, s[6:7]
	global_load_dword v116, v[164:165], off
	v_lshl_add_u64 v[164:165], v[36:37], 0, s[6:7]
	global_load_dword v117, v[164:165], off
	v_lshl_add_u64 v[164:165], v[34:35], 0, s[6:7]
	global_load_dword v118, v[164:165], off
	v_lshl_add_u64 v[164:165], v[32:33], 0, s[6:7]
	global_load_dword v119, v[164:165], off
	v_lshl_add_u64 v[164:165], v[30:31], 0, s[6:7]
	global_load_dword v120, v[164:165], off
	v_lshl_add_u64 v[164:165], v[28:29], 0, s[6:7]
	global_load_dword v121, v[164:165], off
	v_lshl_add_u64 v[164:165], v[26:27], 0, s[6:7]
	global_load_dword v122, v[164:165], off
	v_lshl_add_u64 v[164:165], v[22:23], 0, s[6:7]
	global_load_dword v123, v[164:165], off
	s_add_u32 s6, s6, 0x18000
	s_addc_u32 s7, s7, 0
	v_lshl_add_u64 v[164:165], v[38:39], 0, s[6:7]
	global_load_dword v124, v[164:165], off
	v_lshl_add_u64 v[164:165], v[36:37], 0, s[6:7]
	global_load_dword v125, v[164:165], off
	v_lshl_add_u64 v[164:165], v[34:35], 0, s[6:7]
	global_load_dword v126, v[164:165], off
	v_lshl_add_u64 v[164:165], v[32:33], 0, s[6:7]
	global_load_dword v127, v[164:165], off
	v_lshl_add_u64 v[164:165], v[30:31], 0, s[6:7]
	global_load_dword v128, v[164:165], off
	v_lshl_add_u64 v[164:165], v[28:29], 0, s[6:7]
	global_load_dword v129, v[164:165], off
	v_lshl_add_u64 v[164:165], v[26:27], 0, s[6:7]
	global_load_dword v130, v[164:165], off
	v_lshl_add_u64 v[164:165], v[22:23], 0, s[6:7]
	global_load_dword v131, v[164:165], off
	s_add_u32 s6, s6, 0x18000
	s_addc_u32 s7, s7, 0
	s_andn2_b64 vcc, exec, s[22:23]
	s_cbranch_vccnz .Ltp3_g
	v_lshl_add_u64 v[164:165], s[8:9], 0, v[2:3]
	global_load_dword v132, v[164:165], off
	global_load_dword v140, v[164:165], off offset:64
	global_load_dword v148, v[164:165], off offset:128
	global_load_dword v156, v[164:165], off offset:192
	v_lshl_add_u64 v[164:165], s[8:9], 0, v[24:25]
	global_load_dword v133, v[164:165], off offset:8
	global_load_dword v134, v[164:165], off offset:16
	global_load_dword v135, v[164:165], off offset:24
	global_load_dword v136, v[164:165], off offset:32
	global_load_dword v137, v[164:165], off offset:40
	global_load_dword v138, v[164:165], off offset:48
	global_load_dword v139, v[164:165], off offset:56
	global_load_dword v141, v[164:165], off offset:72
	global_load_dword v142, v[164:165], off offset:80
	global_load_dword v143, v[164:165], off offset:88
	global_load_dword v144, v[164:165], off offset:96
	global_load_dword v145, v[164:165], off offset:104
	global_load_dword v146, v[164:165], off offset:112
	global_load_dword v147, v[164:165], off offset:120
	global_load_dword v149, v[164:165], off offset:136
	global_load_dword v150, v[164:165], off offset:144
	global_load_dword v151, v[164:165], off offset:152
	global_load_dword v152, v[164:165], off offset:160
	global_load_dword v153, v[164:165], off offset:168
	global_load_dword v154, v[164:165], off offset:176
	global_load_dword v155, v[164:165], off offset:184
	global_load_dword v157, v[164:165], off offset:200
	global_load_dword v158, v[164:165], off offset:208
	global_load_dword v159, v[164:165], off offset:216
	global_load_dword v160, v[164:165], off offset:224
	global_load_dword v161, v[164:165], off offset:232
	global_load_dword v162, v[164:165], off offset:240
	global_load_dword v163, v[164:165], off offset:248
	s_waitcnt vmcnt(0)
	v_mul_f32_e32 v100, v100, v132
	v_mul_f32_e32 v101, v101, v133
	v_mul_f32_e32 v102, v102, v134
	v_mul_f32_e32 v103, v103, v135
	v_mul_f32_e32 v104, v104, v136
	v_mul_f32_e32 v105, v105, v137
	v_mul_f32_e32 v106, v106, v138
	v_mul_f32_e32 v107, v107, v139
	v_mul_f32_e32 v108, v108, v140
	v_mul_f32_e32 v109, v109, v141
	v_mul_f32_e32 v110, v110, v142
	v_mul_f32_e32 v111, v111, v143
	v_mul_f32_e32 v112, v112, v144
	v_mul_f32_e32 v113, v113, v145
	v_mul_f32_e32 v114, v114, v146
	v_mul_f32_e32 v115, v115, v147
	v_mul_f32_e32 v116, v116, v148
	v_mul_f32_e32 v117, v117, v149
	v_mul_f32_e32 v118, v118, v150
	v_mul_f32_e32 v119, v119, v151
	v_mul_f32_e32 v120, v120, v152
	v_mul_f32_e32 v121, v121, v153
	v_mul_f32_e32 v122, v122, v154
	v_mul_f32_e32 v123, v123, v155
	v_mul_f32_e32 v124, v124, v156
	v_mul_f32_e32 v125, v125, v157
	v_mul_f32_e32 v126, v126, v158
	v_mul_f32_e32 v127, v127, v159
	v_mul_f32_e32 v128, v128, v160
	v_mul_f32_e32 v129, v129, v161
	v_mul_f32_e32 v130, v130, v162
	v_mul_f32_e32 v131, v131, v163
; DI void transpose_item(const float* W, const float* gain, int K, int Ns, int Nd, int mat, bf16_t* WT, LAS float* scr, int item, int lane) {
;     ...
;     for (int i = 0; i < 32; ++i) { const int kk = 2 * i + (lane >> 5); float v = 0.f; if (sc >= 0) v = W[(size_t)(k0 + kk) * Ns + sc]; if (gain) v *= gain[k0 + kk]; scr[kk * 33 + (lane & 31)] = v; }
.Ltp3_g:
	s_waitcnt vmcnt(0)
	ds_write_b32 v42, v100
	ds_write_b32 v42, v101 offset:264
	ds_write_b32 v42, v102 offset:528
	ds_write_b32 v42, v103 offset:792
	ds_write_b32 v42, v104 offset:1056
	ds_write_b32 v42, v105 offset:1320
	ds_write_b32 v42, v106 offset:1584
	ds_write_b32 v42, v107 offset:1848
	ds_write_b32 v42, v108 offset:2112
	ds_write_b32 v42, v109 offset:2376
	ds_write_b32 v42, v110 offset:2640
	ds_write_b32 v42, v111 offset:2904
	ds_write_b32 v42, v112 offset:3168
	ds_write_b32 v42, v113 offset:3432
	ds_write_b32 v42, v114 offset:3696
	ds_write_b32 v42, v115 offset:3960
	ds_write_b32 v42, v116 offset:4224
	ds_write_b32 v42, v117 offset:4488
	ds_write_b32 v42, v118 offset:4752
	ds_write_b32 v42, v119 offset:5016
	ds_write_b32 v42, v120 offset:5280
	ds_write_b32 v42, v121 offset:5544
	ds_write_b32 v42, v122 offset:5808
	ds_write_b32 v42, v123 offset:6072
	ds_write_b32 v42, v124 offset:6336
	ds_write_b32 v42, v125 offset:6600
	ds_write_b32 v42, v126 offset:6864
	ds_write_b32 v42, v127 offset:7128
	ds_write_b32 v42, v128 offset:7392
	ds_write_b32 v42, v129 offset:7656
	ds_write_b32 v42, v130 offset:7920
	ds_write_b32 v42, v131 offset:8184
	s_add_u32 s8, s8, 0x100
	s_addc_u32 s9, s9, 0
	v_add_u32_e32 v42, 0x2100, v42
	s_cmp_lg_u32 s6, 0x60000
	s_branch .LBB0_104

; DI void transpose_item(const float* W, const float* gain, int K, int Ns, int Nd, int mat, bf16_t* WT, LAS float* scr, int item, int lane) {
;     ...
; #pragma unroll 8
;     for (int i = 0; i < 32; ++i) { const int kk = 2 * i + (lane >> 5); float v = 0.f; if (sc >= 0) v = W[(size_t)(k0 + kk) * Ns + sc]; if (gain) v *= gain[k0 + kk]; scr[kk * 33 + (lane & 31)] = v; }
.LBB0_120:
	v_mov_b32_e32 v100, 0
	v_mov_b32_e32 v101, 0
	v_mov_b32_e32 v102, 0
	v_mov_b32_e32 v103, 0
	v_mov_b32_e32 v104, 0
	v_mov_b32_e32 v105, 0
	v_mov_b32_e32 v106, 0
	v_mov_b32_e32 v107, 0
	v_mov_b32_e32 v108, 0
	v_mov_b32_e32 v109, 0
	v_mov_b32_e32 v110, 0
	v_mov_b32_e32 v111, 0
	v_mov_b32_e32 v112, 0
	v_mov_b32_e32 v113, 0
	v_mov_b32_e32 v114, 0
	v_mov_b32_e32 v115, 0
	v_mov_b32_e32 v116, 0
	v_mov_b32_e32 v117, 0
	v_mov_b32_e32 v118, 0
	v_mov_b32_e32 v119, 0
	v_mov_b32_e32 v120, 0
	v_mov_b32_e32 v121, 0
	v_mov_b32_e32 v122, 0
	v_mov_b32_e32 v123, 0
	v_mov_b32_e32 v124, 0
	v_mov_b32_e32 v125, 0
	v_mov_b32_e32 v126, 0
	v_mov_b32_e32 v127, 0
	v_mov_b32_e32 v128, 0
	v_mov_b32_e32 v129, 0
	v_mov_b32_e32 v130, 0
	v_mov_b32_e32 v131, 0
	s_and_saveexec_b64 s[10:11], s[4:5]
	v_lshl_add_u64 v[164:165], v[38:39], 0, s[24:25]
	global_load_dword v100, v[164:165], off
	v_lshl_add_u64 v[164:165], v[36:37], 0, s[24:25]
	global_load_dword v101, v[164:165], off
	v_lshl_add_u64 v[164:165], v[34:35], 0, s[24:25]
	global_load_dword v102, v[164:165], off
	v_lshl_add_u64 v[164:165], v[32:33], 0, s[24:25]
	global_load_dword v103, v[164:165], off
	v_lshl_add_u64 v[164:165], v[30:31], 0, s[24:25]
	global_load_dword v104, v[164:165], off
	v_lshl_add_u64 v[164:165], v[28:29], 0, s[24:25]
	global_load_dword v105, v[164:165], off
	v_lshl_add_u64 v[164:165], v[26:27], 0, s[24:25]
	global_load_dword v106, v[164:165], off
	v_lshl_add_u64 v[164:165], v[22:23], 0, s[24:25]
	global_load_dword v107, v[164:165], off
	s_add_u32 s24, s24, 0x53000
	s_addc_u32 s25, s25, 0
	v_lshl_add_u64 v[164:165], v[38:39], 0, s[24:25]
	global_load_dword v108, v[164:165], off
	v_lshl_add_u64 v[164:165], v[36:37], 0, s[24:25]
	global_load_dword v109, v[164:165], off
	v_lshl_add_u64 v[164:165], v[34:35], 0, s[24:25]
	global_load_dword v110, v[164:165], off
	v_lshl_add_u64 v[164:165], v[32:33], 0, s[24:25]
	global_load_dword v111, v[164:165], off
	v_lshl_add_u64 v[164:165], v[30:31], 0, s[24:25]
	global_load_dword v112, v[164:165], off
	v_lshl_add_u64 v[164:165], v[28:29], 0, s[24:25]
	global_load_dword v113, v[164:165], off
	v_lshl_add_u64 v[164:165], v[26:27], 0, s[24:25]
	global_load_dword v114, v[164:165], off
	v_lshl_add_u64 v[164:165], v[22:23], 0, s[24:25]
	global_load_dword v115, v[164:165], off
	s_add_u32 s24, s24, 0x53000
	s_addc_u32 s25, s25, 0
	v_lshl_add_u64 v[164:165], v[38:39], 0, s[24:25]
	global_load_dword v116, v[164:165], off
	v_lshl_add_u64 v[164:165], v[36:37], 0, s[24:25]
	global_load_dword v117, v[164:165], off
	v_lshl_add_u64 v[164:165], v[34:35], 0, s[24:25]
	global_load_dword v118, v[164:165], off
	v_lshl_add_u64 v[164:165], v[32:33], 0, s[24:25]
	global_load_dword v119, v[164:165], off
	v_lshl_add_u64 v[164:165], v[30:31], 0, s[24:25]
	global_load_dword v120, v[164:165], off
	v_lshl_add_u64 v[164:165], v[28:29], 0, s[24:25]
	global_load_dword v121, v[164:165], off
	v_lshl_add_u64 v[164:165], v[26:27], 0, s[24:25]
	global_load_dword v122, v[164:165], off
	v_lshl_add_u64 v[164:165], v[22:23], 0, s[24:25]
	global_load_dword v123, v[164:165], off
	s_add_u32 s24, s24, 0x53000
	s_addc_u32 s25, s25, 0
	v_lshl_add_u64 v[164:165], v[38:39], 0, s[24:25]
	global_load_dword v124, v[164:165], off
	v_lshl_add_u64 v[164:165], v[36:37], 0, s[24:25]
	global_load_dword v125, v[164:165], off
	v_lshl_add_u64 v[164:165], v[34:35], 0, s[24:25]
	global_load_dword v126, v[164:165], off
	v_lshl_add_u64 v[164:165], v[32:33], 0, s[24:25]
	global_load_dword v127, v[164:165], off
	v_lshl_add_u64 v[164:165], v[30:31], 0, s[24:25]
	global_load_dword v128, v[164:165], off
	v_lshl_add_u64 v[164:165], v[28:29], 0, s[24:25]
	global_load_dword v129, v[164:165], off
	v_lshl_add_u64 v[164:165], v[26:27], 0, s[24:25]
	global_load_dword v130, v[164:165], off
	v_lshl_add_u64 v[164:165], v[22:23], 0, s[24:25]
	global_load_dword v131, v[164:165], off
	s_add_u32 s24, s24, 0x53000
	s_addc_u32 s25, s25, 0
	s_or_b64 exec, exec, s[10:11]
	s_andn2_b64 vcc, exec, s[26:27]
	s_cbranch_vccnz .Ltp4_g
	v_lshl_add_u64 v[164:165], s[8:9], 0, v[40:41]
	global_load_dword v132, v[164:165], off
	global_load_dword v140, v[164:165], off offset:64
	global_load_dword v148, v[164:165], off offset:128
	global_load_dword v156, v[164:165], off offset:192
	v_lshl_add_u64 v[164:165], s[8:9], 0, v[24:25]
	global_load_dword v133, v[164:165], off offset:8
	global_load_dword v134, v[164:165], off offset:16
	global_load_dword v135, v[164:165], off offset:24
	global_load_dword v136, v[164:165], off offset:32
	global_load_dword v137, v[164:165], off offset:40
	global_load_dword v138, v[164:165], off offset:48
	global_load_dword v139, v[164:165], off offset:56
	global_load_dword v141, v[164:165], off offset:72
	global_load_dword v142, v[164:165], off offset:80
	global_load_dword v143, v[164:165], off offset:88
	global_load_dword v144, v[164:165], off offset:96
	global_load_dword v145, v[164:165], off offset:104
	global_load_dword v146, v[164:165], off offset:112
	global_load_dword v147, v[164:165], off offset:120
	global_load_dword v149, v[164:165], off offset:136
	global_load_dword v150, v[164:165], off offset:144
	global_load_dword v151, v[164:165], off offset:152
	global_load_dword v152, v[164:165], off offset:160
	global_load_dword v153, v[164:165], off offset:168
	global_load_dword v154, v[164:165], off offset:176
	global_load_dword v155, v[164:165], off offset:184
	global_load_dword v157, v[164:165], off offset:200
	global_load_dword v158, v[164:165], off offset:208
	global_load_dword v159, v[164:165], off offset:216
	global_load_dword v160, v[164:165], off offset:224
	global_load_dword v161, v[164:165], off offset:232
	global_load_dword v162, v[164:165], off offset:240
	global_load_dword v163, v[164:165], off offset:248
	s_waitcnt vmcnt(0)
	v_mul_f32_e32 v100, v100, v132
	v_mul_f32_e32 v101, v101, v133
	v_mul_f32_e32 v102, v102, v134
	v_mul_f32_e32 v103, v103, v135
	v_mul_f32_e32 v104, v104, v136
	v_mul_f32_e32 v105, v105, v137
	v_mul_f32_e32 v106, v106, v138
	v_mul_f32_e32 v107, v107, v139
	v_mul_f32_e32 v108, v108, v140
	v_mul_f32_e32 v109, v109, v141
	v_mul_f32_e32 v110, v110, v142
	v_mul_f32_e32 v111, v111, v143
	v_mul_f32_e32 v112, v112, v144
	v_mul_f32_e32 v113, v113, v145
	v_mul_f32_e32 v114, v114, v146
	v_mul_f32_e32 v115, v115, v147
	v_mul_f32_e32 v116, v116, v148
	v_mul_f32_e32 v117, v117, v149
	v_mul_f32_e32 v118, v118, v150
	v_mul_f32_e32 v119, v119, v151
	v_mul_f32_e32 v120, v120, v152
	v_mul_f32_e32 v121, v121, v153
	v_mul_f32_e32 v122, v122, v154
	v_mul_f32_e32 v123, v123, v155
	v_mul_f32_e32 v124, v124, v156
	v_mul_f32_e32 v125, v125, v157
	v_mul_f32_e32 v126, v126, v158
	v_mul_f32_e32 v127, v127, v159
	v_mul_f32_e32 v128, v128, v160
	v_mul_f32_e32 v129, v129, v161
	v_mul_f32_e32 v130, v130, v162
	v_mul_f32_e32 v131, v131, v163
; DI void transpose_item(const float* W, const float* gain, int K, int Ns, int Nd, int mat, bf16_t* WT, LAS float* scr, int item, int lane) {
;     ...
;     for (int i = 0; i < 32; ++i) { const int kk = 2 * i + (lane >> 5); float v = 0.f; if (sc >= 0) v = W[(size_t)(k0 + kk) * Ns + sc]; if (gain) v *= gain[k0 + kk]; scr[kk * 33 + (lane & 31)] = v; }
.Ltp4_g:
	s_waitcnt vmcnt(0)
	ds_write_b32 v2, v100
	ds_write_b32 v2, v101 offset:264
	ds_write_b32 v2, v102 offset:528
	ds_write_b32 v2, v103 offset:792
	ds_write_b32 v2, v104 offset:1056
	ds_write_b32 v2, v105 offset:1320
	ds_write_b32 v2, v106 offset:1584
	ds_write_b32 v2, v107 offset:1848
	ds_write_b32 v2, v108 offset:2112
	ds_write_b32 v2, v109 offset:2376
	ds_write_b32 v2, v110 offset:2640
	ds_write_b32 v2, v111 offset:2904
	ds_write_b32 v2, v112 offset:3168
	ds_write_b32 v2, v113 offset:3432
	ds_write_b32 v2, v114 offset:3696
	ds_write_b32 v2, v115 offset:3960
	ds_write_b32 v2, v116 offset:4224
	ds_write_b32 v2, v117 offset:4488
	ds_write_b32 v2, v118 offset:4752
	ds_write_b32 v2, v119 offset:5016
	ds_write_b32 v2, v120 offset:5280
	ds_write_b32 v2, v121 offset:5544
	ds_write_b32 v2, v122 offset:5808
	ds_write_b32 v2, v123 offset:6072
	ds_write_b32 v2, v124 offset:6336
	ds_write_b32 v2, v125 offset:6600
	ds_write_b32 v2, v126 offset:6864
	ds_write_b32 v2, v127 offset:7128
	ds_write_b32 v2, v128 offset:7392
	ds_write_b32 v2, v129 offset:7656
	ds_write_b32 v2, v130 offset:7920
	ds_write_b32 v2, v131 offset:8184
	s_add_u32 s8, s8, 0x100
	s_addc_u32 s9, s9, 0
	v_add_u32_e32 v2, 0x2100, v2
	s_cmp_lg_u32 s24, 0x14c000
	s_branch .LBB0_8

; DI void transpose_item(const float* W, const float* gain, int K, int Ns, int Nd, int mat, bf16_t* WT, LAS float* scr, int item, int lane) {
;     ...
; #pragma unroll 8
;     for (int i = 0; i < 32; ++i) { const int kk = 2 * i + (lane >> 5); float v = 0.f; if (sc >= 0) v = W[(size_t)(k0 + kk) * Ns + sc]; if (gain) v *= gain[k0 + kk]; scr[kk * 33 + (lane & 31)] = v; }
.LBB0_346:
	v_mov_b32_e32 v100, 0
	v_mov_b32_e32 v101, 0
	v_mov_b32_e32 v102, 0
	v_mov_b32_e32 v103, 0
	v_mov_b32_e32 v104, 0
	v_mov_b32_e32 v105, 0
	v_mov_b32_e32 v106, 0
	v_mov_b32_e32 v107, 0
	v_mov_b32_e32 v108, 0
	v_mov_b32_e32 v109, 0
	v_mov_b32_e32 v110, 0
	v_mov_b32_e32 v111, 0
	v_mov_b32_e32 v112, 0
	v_mov_b32_e32 v113, 0
	v_mov_b32_e32 v114, 0
	v_mov_b32_e32 v115, 0
	v_mov_b32_e32 v116, 0
	v_mov_b32_e32 v117, 0
	v_mov_b32_e32 v118, 0
	v_mov_b32_e32 v119, 0
	v_mov_b32_e32 v120, 0
	v_mov_b32_e32 v121, 0
	v_mov_b32_e32 v122, 0
	v_mov_b32_e32 v123, 0
	v_mov_b32_e32 v124, 0
	v_mov_b32_e32 v125, 0
	v_mov_b32_e32 v126, 0
	v_mov_b32_e32 v127, 0
	v_mov_b32_e32 v128, 0
	v_mov_b32_e32 v129, 0
	v_mov_b32_e32 v130, 0
	v_mov_b32_e32 v131, 0
	s_and_saveexec_b64 s[4:5], s[20:21]
	v_lshl_add_u64 v[164:165], v[22:23], 0, s[22:23]
	global_load_dword v100, v[164:165], off
	v_lshl_add_u64 v[164:165], v[20:21], 0, s[22:23]
	global_load_dword v101, v[164:165], off
	v_lshl_add_u64 v[164:165], v[18:19], 0, s[22:23]
	global_load_dword v102, v[164:165], off
	v_lshl_add_u64 v[164:165], v[16:17], 0, s[22:23]
	global_load_dword v103, v[164:165], off
	v_lshl_add_u64 v[164:165], v[14:15], 0, s[22:23]
	global_load_dword v104, v[164:165], off
	v_lshl_add_u64 v[164:165], v[12:13], 0, s[22:23]
	global_load_dword v105, v[164:165], off
	v_lshl_add_u64 v[164:165], v[10:11], 0, s[22:23]
	global_load_dword v106, v[164:165], off
	v_lshl_add_u64 v[164:165], v[6:7], 0, s[22:23]
	global_load_dword v107, v[164:165], off
	s_add_u32 s22, s22, 0x40000
	s_addc_u32 s23, s23, 0
	v_lshl_add_u64 v[164:165], v[22:23], 0, s[22:23]
	global_load_dword v108, v[164:165], off
	v_lshl_add_u64 v[164:165], v[20:21], 0, s[22:23]
	global_load_dword v109, v[164:165], off
	v_lshl_add_u64 v[164:165], v[18:19], 0, s[22:23]
	global_load_dword v110, v[164:165], off
	v_lshl_add_u64 v[164:165], v[16:17], 0, s[22:23]
	global_load_dword v111, v[164:165], off
	v_lshl_add_u64 v[164:165], v[14:15], 0, s[22:23]
	global_load_dword v112, v[164:165], off
	v_lshl_add_u64 v[164:165], v[12:13], 0, s[22:23]
	global_load_dword v113, v[164:165], off
	v_lshl_add_u64 v[164:165], v[10:11], 0, s[22:23]
	global_load_dword v114, v[164:165], off
	v_lshl_add_u64 v[164:165], v[6:7], 0, s[22:23]
	global_load_dword v115, v[164:165], off
	s_add_u32 s22, s22, 0x40000
	s_addc_u32 s23, s23, 0
	v_lshl_add_u64 v[164:165], v[22:23], 0, s[22:23]
	global_load_dword v116, v[164:165], off
	v_lshl_add_u64 v[164:165], v[20:21], 0, s[22:23]
	global_load_dword v117, v[164:165], off
	v_lshl_add_u64 v[164:165], v[18:19], 0, s[22:23]
	global_load_dword v118, v[164:165], off
	v_lshl_add_u64 v[164:165], v[16:17], 0, s[22:23]
	global_load_dword v119, v[164:165], off
	v_lshl_add_u64 v[164:165], v[14:15], 0, s[22:23]
	global_load_dword v120, v[164:165], off
	v_lshl_add_u64 v[164:165], v[12:13], 0, s[22:23]
	global_load_dword v121, v[164:165], off
	v_lshl_add_u64 v[164:165], v[10:11], 0, s[22:23]
	global_load_dword v122, v[164:165], off
	v_lshl_add_u64 v[164:165], v[6:7], 0, s[22:23]
	global_load_dword v123, v[164:165], off
	s_add_u32 s22, s22, 0x40000
	s_addc_u32 s23, s23, 0
	v_lshl_add_u64 v[164:165], v[22:23], 0, s[22:23]
	global_load_dword v124, v[164:165], off
	v_lshl_add_u64 v[164:165], v[20:21], 0, s[22:23]
	global_load_dword v125, v[164:165], off
	v_lshl_add_u64 v[164:165], v[18:19], 0, s[22:23]
	global_load_dword v126, v[164:165], off
	v_lshl_add_u64 v[164:165], v[16:17], 0, s[22:23]
	global_load_dword v127, v[164:165], off
	v_lshl_add_u64 v[164:165], v[14:15], 0, s[22:23]
	global_load_dword v128, v[164:165], off
	v_lshl_add_u64 v[164:165], v[12:13], 0, s[22:23]
	global_load_dword v129, v[164:165], off
	v_lshl_add_u64 v[164:165], v[10:11], 0, s[22:23]
	global_load_dword v130, v[164:165], off
	v_lshl_add_u64 v[164:165], v[6:7], 0, s[22:23]
	global_load_dword v131, v[164:165], off
	s_add_u32 s22, s22, 0x40000
	s_addc_u32 s23, s23, 0
	s_or_b64 exec, exec, s[4:5]
	s_andn2_b64 vcc, exec, s[24:25]
	s_cbranch_vccnz .Ltp5_g
	v_lshl_add_u64 v[164:165], s[8:9], 0, v[24:25]
	global_load_dword v132, v[164:165], off
	global_load_dword v140, v[164:165], off offset:64
	global_load_dword v148, v[164:165], off offset:128
	global_load_dword v156, v[164:165], off offset:192
	v_lshl_add_u64 v[164:165], s[8:9], 0, v[8:9]
	global_load_dword v133, v[164:165], off offset:8
	global_load_dword v134, v[164:165], off offset:16
	global_load_dword v135, v[164:165], off offset:24
	global_load_dword v136, v[164:165], off offset:32
	global_load_dword v137, v[164:165], off offset:40
	global_load_dword v138, v[164:165], off offset:48
	global_load_dword v139, v[164:165], off offset:56
	global_load_dword v141, v[164:165], off offset:72
	global_load_dword v142, v[164:165], off offset:80
	global_load_dword v143, v[164:165], off offset:88
	global_load_dword v144, v[164:165], off offset:96
	global_load_dword v145, v[164:165], off offset:104
	global_load_dword v146, v[164:165], off offset:112
	global_load_dword v147, v[164:165], off offset:120
	global_load_dword v149, v[164:165], off offset:136
	global_load_dword v150, v[164:165], off offset:144
	global_load_dword v151, v[164:165], off offset:152
	global_load_dword v152, v[164:165], off offset:160
	global_load_dword v153, v[164:165], off offset:168
	global_load_dword v154, v[164:165], off offset:176
	global_load_dword v155, v[164:165], off offset:184
	global_load_dword v157, v[164:165], off offset:200
	global_load_dword v158, v[164:165], off offset:208
	global_load_dword v159, v[164:165], off offset:216
	global_load_dword v160, v[164:165], off offset:224
	global_load_dword v161, v[164:165], off offset:232
	global_load_dword v162, v[164:165], off offset:240
	global_load_dword v163, v[164:165], off offset:248
	s_waitcnt vmcnt(0)
	v_mul_f32_e32 v100, v100, v132
	v_mul_f32_e32 v101, v101, v133
	v_mul_f32_e32 v102, v102, v134
	v_mul_f32_e32 v103, v103, v135
	v_mul_f32_e32 v104, v104, v136
	v_mul_f32_e32 v105, v105, v137
	v_mul_f32_e32 v106, v106, v138
	v_mul_f32_e32 v107, v107, v139
	v_mul_f32_e32 v108, v108, v140
	v_mul_f32_e32 v109, v109, v141
	v_mul_f32_e32 v110, v110, v142
	v_mul_f32_e32 v111, v111, v143
	v_mul_f32_e32 v112, v112, v144
	v_mul_f32_e32 v113, v113, v145
	v_mul_f32_e32 v114, v114, v146
	v_mul_f32_e32 v115, v115, v147
	v_mul_f32_e32 v116, v116, v148
	v_mul_f32_e32 v117, v117, v149
	v_mul_f32_e32 v118, v118, v150
	v_mul_f32_e32 v119, v119, v151
	v_mul_f32_e32 v120, v120, v152
	v_mul_f32_e32 v121, v121, v153
	v_mul_f32_e32 v122, v122, v154
	v_mul_f32_e32 v123, v123, v155
	v_mul_f32_e32 v124, v124, v156
	v_mul_f32_e32 v125, v125, v157
	v_mul_f32_e32 v126, v126, v158
	v_mul_f32_e32 v127, v127, v159
	v_mul_f32_e32 v128, v128, v160
	v_mul_f32_e32 v129, v129, v161
	v_mul_f32_e32 v130, v130, v162
	v_mul_f32_e32 v131, v131, v163
; DI void transpose_item(const float* W, const float* gain, int K, int Ns, int Nd, int mat, bf16_t* WT, LAS float* scr, int item, int lane) {
;     ...
;     for (int i = 0; i < 32; ++i) { const int kk = 2 * i + (lane >> 5); float v = 0.f; if (sc >= 0) v = W[(size_t)(k0 + kk) * Ns + sc]; if (gain) v *= gain[k0 + kk]; scr[kk * 33 + (lane & 31)] = v; }
.Ltp5_g:
	s_waitcnt vmcnt(0)
	ds_write_b32 v0, v100
	ds_write_b32 v0, v101 offset:264
	ds_write_b32 v0, v102 offset:528
	ds_write_b32 v0, v103 offset:792
	ds_write_b32 v0, v104 offset:1056
	ds_write_b32 v0, v105 offset:1320
	ds_write_b32 v0, v106 offset:1584
	ds_write_b32 v0, v107 offset:1848
	ds_write_b32 v0, v108 offset:2112
	ds_write_b32 v0, v109 offset:2376
	ds_write_b32 v0, v110 offset:2640
	ds_write_b32 v0, v111 offset:2904
	ds_write_b32 v0, v112 offset:3168
	ds_write_b32 v0, v113 offset:3432
	ds_write_b32 v0, v114 offset:3696
	ds_write_b32 v0, v115 offset:3960
	ds_write_b32 v0, v116 offset:4224
	ds_write_b32 v0, v117 offset:4488
	ds_write_b32 v0, v118 offset:4752
	ds_write_b32 v0, v119 offset:5016
	ds_write_b32 v0, v120 offset:5280
	ds_write_b32 v0, v121 offset:5544
	ds_write_b32 v0, v122 offset:5808
	ds_write_b32 v0, v123 offset:6072
	ds_write_b32 v0, v124 offset:6336
	ds_write_b32 v0, v125 offset:6600
	ds_write_b32 v0, v126 offset:6864
	ds_write_b32 v0, v127 offset:7128
	ds_write_b32 v0, v128 offset:7392
	ds_write_b32 v0, v129 offset:7656
	ds_write_b32 v0, v130 offset:7920
	ds_write_b32 v0, v131 offset:8184
	s_add_u32 s8, s8, 0x100
	s_addc_u32 s9, s9, 0
	v_add_u32_e32 v0, 0x2100, v0
	s_cmp_lg_u32 s22, 0x100000
	s_branch .LBB0_335
